# v23 with one static s_setprio 1 for waves 4-7 around the attention loops and no per-phase flips
# baseline (speedup 1.0000x reference)
.LBB0_1038:
	s_or_b64 exec, exec, s[4:5]
	v_and_b32_e32 v0, 0x60, v26
	s_movk_i32 s4, 0x90
	v_lshlrev_b32_e32 v2, 3, v32
	v_mad_u32_u24 v207, v203, s4, 0
	v_mad_u64_u32 v[0:1], s[4:5], v28, s4, v[0:1]
	v_and_or_b32 v0, v2, 8, v0
	v_lshlrev_b32_e32 v1, 6, v203
	v_add_u32_e32 v208, 0, v0
	v_add3_u32 v204, v207, v1, v184
	v_add_u32_e32 v1, 0, v4
	v_add_u32_e32 v205, 0x9800, v208
	s_waitcnt vmcnt(3)
	ds_write_b128 v1, v[8:11] offset:13312
	s_waitcnt vmcnt(2)
	ds_write2_b64 v205, v[16:17], v[18:19] offset0:128 offset1:130
	s_waitcnt lgkmcnt(0)
	s_barrier
	ds_read_b128 v[0:3], v204
	ds_read_b128 v[4:7], v204 offset:32
	ds_read_b128 v[8:11], v204 offset:6656
	ds_read_b128 v[12:15], v204 offset:6688
	ds_read_b128 v[16:19], v204 offset:64
	ds_read_b128 v[28:31], v204 offset:96
	ds_read_b128 v[64:67], v204 offset:6720
	ds_read_b128 v[68:71], v204 offset:6752
	ds_read_b128 v[72:75], v204 offset:128
	ds_read_b128 v[76:79], v204 offset:160
	ds_read_b128 v[80:83], v204 offset:6784
	ds_read_b128 v[84:87], v204 offset:6816
	s_mov_b32 s91, 2
	s_lshl_b32 s87, s6, 2
	s_waitcnt lgkmcnt(11)
	v_mfma_f32_32x32x16_bf16 v[48:63], v[0:3], v[100:103], 0
	s_mov_b32 s79, 0
	s_waitcnt lgkmcnt(9)
	v_mfma_f32_32x32x16_bf16 v[32:47], v[8:11], v[100:103], 0
	v_mfma_f32_32x32x16_bf16 v[48:63], v[4:7], v[104:107], v[48:63]
	s_waitcnt lgkmcnt(8)
	v_mfma_f32_32x32x16_bf16 v[32:47], v[12:15], v[104:107], v[32:47]
	s_waitcnt lgkmcnt(7)
	v_mfma_f32_32x32x16_bf16 v[48:63], v[16:19], v[108:111], v[48:63]
	s_waitcnt lgkmcnt(5)
	v_mfma_f32_32x32x16_bf16 v[32:47], v[64:67], v[108:111], v[32:47]
	v_mfma_f32_32x32x16_bf16 v[48:63], v[28:31], v[112:115], v[48:63]
	s_waitcnt lgkmcnt(4)
	v_mfma_f32_32x32x16_bf16 v[32:47], v[68:71], v[112:115], v[32:47]
	s_waitcnt lgkmcnt(3)
	v_mfma_f32_32x32x16_bf16 v[48:63], v[72:75], v[116:119], v[48:63]
	s_waitcnt lgkmcnt(1)
	v_mfma_f32_32x32x16_bf16 v[32:47], v[80:83], v[116:119], v[32:47]
	v_mfma_f32_32x32x16_bf16 v[48:63], v[76:79], v[120:123], v[48:63]
	s_waitcnt lgkmcnt(0)
	v_mfma_f32_32x32x16_bf16 v[32:47], v[84:87], v[120:123], v[32:47]
	ds_read_b128 v[172:175], v204 offset:13312
	ds_read_b128 v[152:155], v204 offset:13344
	ds_read_b128 v[180:183], v204 offset:19968
	ds_read_b128 v[164:167], v204 offset:20000
	ds_read_b128 v[156:159], v204 offset:13376
	ds_read_b128 v[140:143], v204 offset:13408
	ds_read_b128 v[176:179], v204 offset:20032
	ds_read_b128 v[160:163], v204 offset:20064
	ds_read_b128 v[148:151], v204 offset:13440
	ds_read_b128 v[136:139], v204 offset:13472
	ds_read_b128 v[168:171], v204 offset:20096
	ds_read_b128 v[144:147], v204 offset:20128
	s_add_u32 s4, s60, 0x100
	v_lshl_add_u64 v[0:1], s[60:61], 0, v[24:25]
	v_mov_b32_e32 v27, v97
	s_addc_u32 s5, 0, 0
	v_lshl_add_u64 v[190:191], v[0:1], 0, v[26:27]
	v_lshl_add_u64 v[0:1], s[4:5], 0, v[24:25]
	v_mov_b32_e32 v199, 0
	v_lshl_add_u64 v[188:189], s[96:97], 0, v[20:21]
	v_lshl_add_u64 v[186:187], s[96:97], 0, v[22:23]
	v_lshl_add_u64 v[98:99], v[0:1], 0, v[26:27]
	s_add_u32 s98, s94, 0x12209000
	s_addc_u32 s99, s95, 0
	s_add_u32 s100, s94, 0x11200000
	s_addc_u32 s101, s95, 0

	v_exp_f32_e32 v48, v48
	v_exp_f32_e32 v49, v49
	v_exp_f32_e32 v50, v50
	v_add_f32_e32 v195, v48, v49
	v_exp_f32_e32 v51, v51
	v_add_f32_e32 v195, v50, v195
	v_exp_f32_e32 v52, v52
	v_add_f32_e32 v195, v51, v195
	v_exp_f32_e32 v53, v53
	v_add_f32_e32 v195, v52, v195
	v_exp_f32_e32 v54, v54
	v_add_f32_e32 v195, v53, v195
	v_exp_f32_e32 v55, v55
	v_add_f32_e32 v195, v54, v195
	v_exp_f32_e32 v56, v56
	v_add_f32_e32 v195, v55, v195
	v_exp_f32_e32 v57, v57
	v_add_f32_e32 v195, v56, v195
	v_exp_f32_e32 v58, v58
	v_add_f32_e32 v195, v57, v195
	v_exp_f32_e32 v59, v59
	v_add_f32_e32 v195, v58, v195
	v_exp_f32_e32 v60, v60
	v_add_f32_e32 v195, v59, v195
	v_exp_f32_e32 v61, v61
	v_add_f32_e32 v195, v60, v195
	v_exp_f32_e32 v62, v62
	v_add_f32_e32 v195, v61, v195
	v_exp_f32_e32 v63, v63
	v_add_f32_e32 v195, v62, v195
	v_add_f32_e32 v195, v63, v195
	s_movk_i32 s93, 0xbf
	v_mov_b32_e32 v0, 0
	v_mov_b32_e32 v1, v199
	v_mov_b32_e32 v2, v199
	v_mov_b32_e32 v3, v199
	v_mov_b32_e32 v4, v199
	v_mov_b32_e32 v5, v199
	v_mov_b32_e32 v6, v199
	v_mov_b32_e32 v7, v199
	v_mov_b32_e32 v8, v199
	v_mov_b32_e32 v9, v199
	v_mov_b32_e32 v10, v199
	v_mov_b32_e32 v11, v199
	v_mov_b32_e32 v12, v199
	v_mov_b32_e32 v13, v199
	v_mov_b32_e32 v14, v199
	v_mov_b32_e32 v15, v199
	v_mov_b32_e32 v16, 0
	v_mov_b32_e32 v17, v199
	v_mov_b32_e32 v18, v199
	v_mov_b32_e32 v19, v199
	v_mov_b32_e32 v20, v199
	v_mov_b32_e32 v21, v199
	v_mov_b32_e32 v22, v199
	v_mov_b32_e32 v23, v199
	v_mov_b32_e32 v24, v199
	v_mov_b32_e32 v25, v199
	v_mov_b32_e32 v26, v199
	v_mov_b32_e32 v27, v199
	v_mov_b32_e32 v28, v199
	v_mov_b32_e32 v29, v199
	v_mov_b32_e32 v30, v199
	v_mov_b32_e32 v31, v199
	s_cmp_ge_u32 s86, 0x80
	s_cbranch_scc0 .LatA_noprio
	s_setprio 1
.LatA_noprio:


.LatA_h0:
	s_or_b64 exec, exec, s[4:5]
	global_load_dwordx4 v[132:135], v[200:201], off offset:256

	s_waitcnt lgkmcnt(7)
	v_mfma_f32_32x32x16_bf16 v[80:95], v[176:179], v[108:111], v[80:95]
	v_add_f32_e32 v251, v39, v251
	v_cvt_pk_bf16_f32 v51, v54, v55
	v_exp_f32_e32 v41, v41
	v_add_f32_e32 v251, v40, v251
	v_mfma_f32_32x32x16_bf16 v[64:79], v[140:143], v[112:115], v[64:79]
	v_exp_f32_e32 v42, v42
	v_add_f32_e32 v251, v41, v251
	v_cvt_pk_bf16_f32 v52, v56, v57
	v_exp_f32_e32 v43, v43
	s_waitcnt lgkmcnt(6)
	v_mfma_f32_32x32x16_bf16 v[80:95], v[160:163], v[112:115], v[80:95]
	v_add_f32_e32 v251, v42, v251
	v_exp_f32_e32 v44, v44
	v_add_f32_e32 v251, v43, v251
	v_cvt_pk_bf16_f32 v53, v58, v59
	s_waitcnt lgkmcnt(5)
	v_mfma_f32_32x32x16_bf16 v[64:79], v[148:151], v[116:119], v[64:79]
	v_exp_f32_e32 v45, v45
	v_add_f32_e32 v251, v44, v251
	v_exp_f32_e32 v46, v46
	v_add_f32_e32 v251, v45, v251
	v_add_u32_e32 v198, v207, v184
	ds_read_b128 v[210:213], v198 offset:44544
	ds_read_b128 v[214:217], v198 offset:39936
	ds_read_b128 v[218:221], v198 offset:39968
	ds_read_b128 v[222:225], v198 offset:44576
	ds_read_b128 v[226:229], v198 offset:40000
	ds_read_b128 v[230:233], v198 offset:44608
	ds_read_b128 v[234:237], v198 offset:40032
	ds_read_b128 v[238:241], v198 offset:44640
	s_waitcnt lgkmcnt(11)
	v_mfma_f32_32x32x16_bf16 v[80:95], v[168:171], v[116:119], v[80:95]
	v_cvt_pk_bf16_f32 v54, v60, v61
	v_exp_f32_e32 v47, v47
	v_add_f32_e32 v251, v46, v251
	v_add_f32_e32 v251, v47, v251
	v_mfma_f32_32x32x16_bf16 v[64:79], v[136:139], v[120:123], v[64:79]
	v_cvt_pk_bf16_f32 v55, v62, v63
	v_cvt_pk_bf16_f32 v32, v32, v33
	v_cvt_pk_bf16_f32 v33, v34, v35
	v_cvt_pk_bf16_f32 v34, v36, v37
	v_cvt_pk_bf16_f32 v35, v38, v39
	v_cvt_pk_bf16_f32 v36, v40, v41
	s_waitcnt lgkmcnt(10)
	v_mfma_f32_32x32x16_bf16 v[80:95], v[144:147], v[120:123], v[80:95]
	v_cvt_pk_bf16_f32 v37, v42, v43
	v_cvt_pk_bf16_f32 v38, v44, v45
	v_cvt_pk_bf16_f32 v39, v46, v47
	v_add_f32_e32 v195, v195, v251
	v_add_f32_e32 v199, v199, v195
	s_waitcnt lgkmcnt(0)
	s_barrier

	v_add_u32_e32 v197, s6, v204
	v_mfma_f32_32x32x16_bf16 v[0:15], v[48:51], v[210:213], v[0:15]
	ds_read_b128 v[172:175], v197
	ds_read_b128 v[152:155], v197 offset:32
	v_mfma_f32_32x32x16_bf16 v[0:15], v[52:55], v[222:225], v[0:15]
	ds_read_b128 v[180:183], v197 offset:6656
	ds_read_b128 v[164:167], v197 offset:6688
	v_mfma_f32_32x32x16_bf16 v[0:15], v[32:35], v[230:233], v[0:15]
	ds_read_b128 v[156:159], v197 offset:64
	ds_read_b128 v[140:143], v197 offset:96
	v_exp_f32_e32 v64, v64
	v_exp_f32_e32 v65, v65
	v_exp_f32_e32 v66, v66
	v_add_f32_e32 v195, v64, v65
	v_mfma_f32_32x32x16_bf16 v[0:15], v[36:39], v[238:241], v[0:15]
	ds_read_b128 v[176:179], v197 offset:6720
	ds_read_b128 v[160:163], v197 offset:6752
	v_exp_f32_e32 v67, v67
	v_add_f32_e32 v195, v66, v195
	v_exp_f32_e32 v68, v68
	v_add_f32_e32 v195, v67, v195
	v_exp_f32_e32 v69, v69
	v_add_f32_e32 v195, v68, v195
	v_mfma_f32_32x32x16_bf16 v[16:31], v[48:51], v[214:217], v[16:31]
	ds_read_b128 v[148:151], v197 offset:128
	ds_read_b128 v[136:139], v197 offset:160
	v_exp_f32_e32 v70, v70
	v_add_f32_e32 v195, v69, v195
	v_exp_f32_e32 v71, v71
	v_add_f32_e32 v195, v70, v195
	v_exp_f32_e32 v72, v72
	v_mfma_f32_32x32x16_bf16 v[16:31], v[52:55], v[218:221], v[16:31]
	ds_read_b128 v[168:171], v197 offset:6784
	ds_read_b128 v[144:147], v197 offset:6816
	v_add_f32_e32 v195, v71, v195
	v_exp_f32_e32 v73, v73
	v_add_f32_e32 v195, v72, v195
	v_exp_f32_e32 v74, v74
	v_add_f32_e32 v195, v73, v195
	v_mfma_f32_32x32x16_bf16 v[16:31], v[32:35], v[226:229], v[16:31]
	v_exp_f32_e32 v75, v75
	v_add_f32_e32 v195, v74, v195
	v_exp_f32_e32 v76, v76
	v_add_f32_e32 v195, v75, v195
	v_exp_f32_e32 v77, v77
	v_mfma_f32_32x32x16_bf16 v[16:31], v[36:39], v[234:237], v[16:31]
	v_add_f32_e32 v195, v76, v195
	v_exp_f32_e32 v78, v78
	v_add_f32_e32 v195, v77, v195
	v_exp_f32_e32 v79, v79
	v_add_f32_e32 v195, v78, v195
	v_add_f32_e32 v195, v79, v195
	s_waitcnt lgkmcnt(11)
	v_mfma_f32_32x32x16_bf16 v[48:63], v[172:175], v[100:103], 0
	v_exp_f32_e32 v80, v80
	v_exp_f32_e32 v81, v81
	v_exp_f32_e32 v82, v82
	s_waitcnt lgkmcnt(9)
	v_mfma_f32_32x32x16_bf16 v[32:47], v[180:183], v[100:103], 0
	v_add_f32_e32 v251, v80, v81
	v_cvt_pk_bf16_f32 v64, v64, v65
	v_exp_f32_e32 v83, v83
	v_add_f32_e32 v251, v82, v251
	v_mfma_f32_32x32x16_bf16 v[48:63], v[152:155], v[104:107], v[48:63]
	v_exp_f32_e32 v84, v84
	v_add_f32_e32 v251, v83, v251
	v_cvt_pk_bf16_f32 v65, v66, v67
	v_exp_f32_e32 v85, v85
	s_waitcnt lgkmcnt(8)
	v_mfma_f32_32x32x16_bf16 v[32:47], v[164:167], v[104:107], v[32:47]
	v_add_f32_e32 v251, v84, v251
	v_exp_f32_e32 v86, v86
	v_add_f32_e32 v251, v85, v251
	v_cvt_pk_bf16_f32 v66, v68, v69
	s_waitcnt lgkmcnt(7)
	v_mfma_f32_32x32x16_bf16 v[48:63], v[156:159], v[108:111], v[48:63]
	v_exp_f32_e32 v87, v87
	v_add_f32_e32 v251, v86, v251
	v_exp_f32_e32 v88, v88
	s_add_i32 s4, s91, 1
	s_cmp_lg_u32 s91, 2
	s_cselect_b32 s74, s4, 0
	s_mul_i32 s6, s74, 0x3400
	s_add_i32 s7, s6, 0
	s_add_u32 s98, s98, 0x3000
	s_addc_u32 s99, s99, 0

	v_add_u32_e32 v253, s7, v96
	s_waitcnt vmcnt(1)
	ds_write_b128 v253, v[128:131]
	s_and_saveexec_b64 s[4:5], s[2:3]
	v_add_u32_e32 v253, s7, v185
	ds_write_b128 v253, v[124:127]
	s_or_b64 exec, exec, s[4:5]
	v_lshl_add_u64 v[200:201], s[100:101], 0, v[190:191]

	s_waitcnt vmcnt(0)
	ds_write2_b64 v205, v[132:133], v[134:135] offset0:128 offset1:130
	v_lshl_add_u64 v[128:129], s[98:99], 0, v[188:189]
	s_nop 0
	global_load_dwordx4 v[128:131], v[128:129], off

	s_and_saveexec_b64 s[4:5], s[2:3]
	s_cbranch_execz .LatA_h1
	v_lshl_add_u64 v[124:125], s[98:99], 0, v[186:187]
	s_nop 0
	global_load_dwordx4 v[124:127], v[124:125], off
.LatA_h1:
	s_or_b64 exec, exec, s[4:5]
	global_load_dwordx4 v[132:135], v[200:201], off offset:384

	s_sub_u32 s98, s98, 0x3000
	s_subb_u32 s99, s99, 0

	s_waitcnt lgkmcnt(7)
	v_mfma_f32_32x32x16_bf16 v[32:47], v[176:179], v[108:111], v[32:47]
	v_add_f32_e32 v251, v87, v251
	v_cvt_pk_bf16_f32 v67, v70, v71
	v_exp_f32_e32 v89, v89
	v_add_f32_e32 v251, v88, v251
	v_mfma_f32_32x32x16_bf16 v[48:63], v[140:143], v[112:115], v[48:63]
	v_exp_f32_e32 v90, v90
	v_add_f32_e32 v251, v89, v251
	v_cvt_pk_bf16_f32 v68, v72, v73
	v_exp_f32_e32 v91, v91
	s_waitcnt lgkmcnt(6)
	v_mfma_f32_32x32x16_bf16 v[32:47], v[160:163], v[112:115], v[32:47]
	v_add_f32_e32 v251, v90, v251
	v_exp_f32_e32 v92, v92
	v_add_f32_e32 v251, v91, v251
	v_cvt_pk_bf16_f32 v69, v74, v75
	s_waitcnt lgkmcnt(5)
	v_mfma_f32_32x32x16_bf16 v[48:63], v[148:151], v[116:119], v[48:63]
	v_exp_f32_e32 v93, v93
	v_add_f32_e32 v251, v92, v251
	v_exp_f32_e32 v94, v94
	v_add_f32_e32 v251, v93, v251
	v_add_u32_e32 v198, v207, v184
	ds_read_b128 v[210:213], v198 offset:53760
	ds_read_b128 v[214:217], v198 offset:49152
	ds_read_b128 v[218:221], v198 offset:49184
	ds_read_b128 v[222:225], v198 offset:53792
	ds_read_b128 v[226:229], v198 offset:49216
	ds_read_b128 v[230:233], v198 offset:53824
	ds_read_b128 v[234:237], v198 offset:49248
	ds_read_b128 v[238:241], v198 offset:53856
	s_waitcnt lgkmcnt(11)
	v_mfma_f32_32x32x16_bf16 v[32:47], v[168:171], v[116:119], v[32:47]
	v_cvt_pk_bf16_f32 v70, v76, v77
	v_exp_f32_e32 v95, v95
	v_add_f32_e32 v251, v94, v251
	v_add_f32_e32 v251, v95, v251
	v_mfma_f32_32x32x16_bf16 v[48:63], v[136:139], v[120:123], v[48:63]
	v_cvt_pk_bf16_f32 v71, v78, v79
	v_cvt_pk_bf16_f32 v80, v80, v81
	v_cvt_pk_bf16_f32 v81, v82, v83
	v_cvt_pk_bf16_f32 v82, v84, v85
	v_cvt_pk_bf16_f32 v83, v86, v87
	v_cvt_pk_bf16_f32 v84, v88, v89
	s_waitcnt lgkmcnt(10)
	v_mfma_f32_32x32x16_bf16 v[32:47], v[144:147], v[120:123], v[32:47]
	v_cvt_pk_bf16_f32 v85, v90, v91
	v_cvt_pk_bf16_f32 v86, v92, v93
	v_cvt_pk_bf16_f32 v87, v94, v95
	v_add_f32_e32 v195, v195, v251
	v_add_f32_e32 v199, v199, v195
	s_add_i32 s92, s79, 2
	s_waitcnt lgkmcnt(0)
	s_barrier

	s_cmp_ge_u32 s92, s87
	s_cbranch_scc1 .LatA_yplain

	v_add_u32_e32 v197, s6, v204
	v_mfma_f32_32x32x16_bf16 v[0:15], v[64:67], v[210:213], v[0:15]
	ds_read_b128 v[172:175], v197
	ds_read_b128 v[152:155], v197 offset:32
	v_mfma_f32_32x32x16_bf16 v[0:15], v[68:71], v[222:225], v[0:15]
	ds_read_b128 v[180:183], v197 offset:6656
	ds_read_b128 v[164:167], v197 offset:6688
	v_mfma_f32_32x32x16_bf16 v[0:15], v[80:83], v[230:233], v[0:15]
	ds_read_b128 v[156:159], v197 offset:64
	ds_read_b128 v[140:143], v197 offset:96
	v_exp_f32_e32 v48, v48
	v_exp_f32_e32 v49, v49
	v_exp_f32_e32 v50, v50
	v_add_f32_e32 v195, v48, v49
	v_mfma_f32_32x32x16_bf16 v[0:15], v[84:87], v[238:241], v[0:15]
	ds_read_b128 v[176:179], v197 offset:6720
	ds_read_b128 v[160:163], v197 offset:6752
	v_exp_f32_e32 v51, v51
	v_add_f32_e32 v195, v50, v195
	v_exp_f32_e32 v52, v52
	v_add_f32_e32 v195, v51, v195
	v_exp_f32_e32 v53, v53
	v_add_f32_e32 v195, v52, v195
	v_mfma_f32_32x32x16_bf16 v[16:31], v[64:67], v[214:217], v[16:31]
	ds_read_b128 v[148:151], v197 offset:128
	ds_read_b128 v[136:139], v197 offset:160
	v_exp_f32_e32 v54, v54
	v_add_f32_e32 v195, v53, v195
	v_exp_f32_e32 v55, v55
	v_add_f32_e32 v195, v54, v195
	v_exp_f32_e32 v56, v56
	v_mfma_f32_32x32x16_bf16 v[16:31], v[68:71], v[218:221], v[16:31]
	ds_read_b128 v[168:171], v197 offset:6784
	ds_read_b128 v[144:147], v197 offset:6816
	v_add_f32_e32 v195, v55, v195
	v_exp_f32_e32 v57, v57
	v_add_f32_e32 v195, v56, v195
	v_exp_f32_e32 v58, v58
	v_add_f32_e32 v195, v57, v195
	v_mfma_f32_32x32x16_bf16 v[16:31], v[80:83], v[226:229], v[16:31]
	v_exp_f32_e32 v59, v59
	v_add_f32_e32 v195, v58, v195
	v_exp_f32_e32 v60, v60
	v_add_f32_e32 v195, v59, v195
	v_exp_f32_e32 v61, v61
	v_mfma_f32_32x32x16_bf16 v[16:31], v[84:87], v[234:237], v[16:31]
	v_add_f32_e32 v195, v60, v195
	v_exp_f32_e32 v62, v62
	v_add_f32_e32 v195, v61, v195
	v_exp_f32_e32 v63, v63
	v_add_f32_e32 v195, v62, v195
	v_add_f32_e32 v195, v63, v195
	s_branch .LatA_ctl
.LatA_yplain:
	v_add_u32_e32 v197, s6, v204
	v_mfma_f32_32x32x16_bf16 v[0:15], v[64:67], v[210:213], v[0:15]
	ds_read_b128 v[172:175], v197
	ds_read_b128 v[152:155], v197 offset:32
	v_mfma_f32_32x32x16_bf16 v[0:15], v[68:71], v[222:225], v[0:15]
	ds_read_b128 v[180:183], v197 offset:6656
	ds_read_b128 v[164:167], v197 offset:6688
	v_mfma_f32_32x32x16_bf16 v[0:15], v[80:83], v[230:233], v[0:15]
	ds_read_b128 v[156:159], v197 offset:64
	ds_read_b128 v[140:143], v197 offset:96
	v_mfma_f32_32x32x16_bf16 v[0:15], v[84:87], v[238:241], v[0:15]
	ds_read_b128 v[176:179], v197 offset:6720
	ds_read_b128 v[160:163], v197 offset:6752
	v_mfma_f32_32x32x16_bf16 v[16:31], v[64:67], v[214:217], v[16:31]
	ds_read_b128 v[148:151], v197 offset:128
	ds_read_b128 v[136:139], v197 offset:160
	v_mfma_f32_32x32x16_bf16 v[16:31], v[68:71], v[218:221], v[16:31]
	ds_read_b128 v[168:171], v197 offset:6784
	ds_read_b128 v[144:147], v197 offset:6816
	v_mfma_f32_32x32x16_bf16 v[16:31], v[80:83], v[226:229], v[16:31]
	v_mfma_f32_32x32x16_bf16 v[16:31], v[84:87], v[234:237], v[16:31]

.LatA_prioexit:
	s_setprio 0
	s_branch .LBB0_1049


.LBB0_1106:
	s_cmp_ge_u32 s86, 0x80
	s_cbranch_scc0 .LatB_noprio
	s_setprio 1

.LatB_h0:
	s_or_b64 exec, exec, s[4:5]
	global_load_dwordx4 v[132:135], v[200:201], off offset:256

	s_waitcnt lgkmcnt(7)
	v_mfma_f32_32x32x16_bf16 v[80:95], v[176:179], v[108:111], v[80:95]
	v_add_f32_e32 v251, v39, v251
	v_cvt_pk_bf16_f32 v51, v54, v55
	v_exp_f32_e32 v41, v41
	v_add_f32_e32 v251, v40, v251
	v_mfma_f32_32x32x16_bf16 v[64:79], v[140:143], v[112:115], v[64:79]
	v_exp_f32_e32 v42, v42
	v_add_f32_e32 v251, v41, v251
	v_cvt_pk_bf16_f32 v52, v56, v57
	v_exp_f32_e32 v43, v43
	s_waitcnt lgkmcnt(6)
	v_mfma_f32_32x32x16_bf16 v[80:95], v[160:163], v[112:115], v[80:95]
	v_add_f32_e32 v251, v42, v251
	v_exp_f32_e32 v44, v44
	v_add_f32_e32 v251, v43, v251
	v_cvt_pk_bf16_f32 v53, v58, v59
	s_waitcnt lgkmcnt(5)
	v_mfma_f32_32x32x16_bf16 v[64:79], v[148:151], v[116:119], v[64:79]
	v_exp_f32_e32 v45, v45
	v_add_f32_e32 v251, v44, v251
	v_exp_f32_e32 v46, v46
	v_add_f32_e32 v251, v45, v251
	v_add_u32_e32 v196, v208, v184
	ds_read_b128 v[212:215], v196 offset:44544
	ds_read_b128 v[216:219], v196 offset:39936
	ds_read_b128 v[220:223], v196 offset:39968
	ds_read_b128 v[224:227], v196 offset:44576
	ds_read_b128 v[228:231], v196 offset:40000
	ds_read_b128 v[232:235], v196 offset:44608
	ds_read_b128 v[236:239], v196 offset:40032
	ds_read_b128 v[240:243], v196 offset:44640
	s_waitcnt lgkmcnt(11)
	v_mfma_f32_32x32x16_bf16 v[80:95], v[168:171], v[116:119], v[80:95]
	v_cvt_pk_bf16_f32 v54, v60, v61
	v_exp_f32_e32 v47, v47
	v_add_f32_e32 v251, v46, v251
	v_add_f32_e32 v251, v47, v251
	v_mfma_f32_32x32x16_bf16 v[64:79], v[136:139], v[120:123], v[64:79]
	v_cvt_pk_bf16_f32 v55, v62, v63
	v_cvt_pk_bf16_f32 v32, v32, v33
	v_cvt_pk_bf16_f32 v33, v34, v35
	v_cvt_pk_bf16_f32 v34, v36, v37
	v_cvt_pk_bf16_f32 v35, v38, v39
	v_cvt_pk_bf16_f32 v36, v40, v41
	s_waitcnt lgkmcnt(10)
	v_mfma_f32_32x32x16_bf16 v[80:95], v[144:147], v[120:123], v[80:95]
	v_cvt_pk_bf16_f32 v37, v42, v43
	v_cvt_pk_bf16_f32 v38, v44, v45
	v_cvt_pk_bf16_f32 v39, v46, v47
	v_add_f32_e32 v195, v195, v251
	v_add_f32_e32 v198, v198, v195
	s_waitcnt lgkmcnt(0)
	s_barrier

	v_add_u32_e32 v197, s6, v209
	v_mfma_f32_32x32x16_bf16 v[0:15], v[48:51], v[212:215], v[0:15]
	ds_read_b128 v[172:175], v197
	ds_read_b128 v[152:155], v197 offset:32
	v_mfma_f32_32x32x16_bf16 v[0:15], v[52:55], v[224:227], v[0:15]
	ds_read_b128 v[180:183], v197 offset:6656
	ds_read_b128 v[164:167], v197 offset:6688
	v_mfma_f32_32x32x16_bf16 v[0:15], v[32:35], v[232:235], v[0:15]
	ds_read_b128 v[156:159], v197 offset:64
	ds_read_b128 v[140:143], v197 offset:96
	v_exp_f32_e32 v64, v64
	v_exp_f32_e32 v65, v65
	v_exp_f32_e32 v66, v66
	v_add_f32_e32 v195, v64, v65
	v_mfma_f32_32x32x16_bf16 v[0:15], v[36:39], v[240:243], v[0:15]
	ds_read_b128 v[176:179], v197 offset:6720
	ds_read_b128 v[160:163], v197 offset:6752
	v_exp_f32_e32 v67, v67
	v_add_f32_e32 v195, v66, v195
	v_exp_f32_e32 v68, v68
	v_add_f32_e32 v195, v67, v195
	v_exp_f32_e32 v69, v69
	v_add_f32_e32 v195, v68, v195
	v_mfma_f32_32x32x16_bf16 v[16:31], v[48:51], v[216:219], v[16:31]
	ds_read_b128 v[148:151], v197 offset:128
	ds_read_b128 v[136:139], v197 offset:160
	v_exp_f32_e32 v70, v70
	v_add_f32_e32 v195, v69, v195
	v_exp_f32_e32 v71, v71
	v_add_f32_e32 v195, v70, v195
	v_exp_f32_e32 v72, v72
	v_mfma_f32_32x32x16_bf16 v[16:31], v[52:55], v[220:223], v[16:31]
	ds_read_b128 v[168:171], v197 offset:6784
	ds_read_b128 v[144:147], v197 offset:6816
	v_add_f32_e32 v195, v71, v195
	v_exp_f32_e32 v73, v73
	v_add_f32_e32 v195, v72, v195
	v_exp_f32_e32 v74, v74
	v_add_f32_e32 v195, v73, v195
	v_mfma_f32_32x32x16_bf16 v[16:31], v[32:35], v[228:231], v[16:31]
	v_exp_f32_e32 v75, v75
	v_add_f32_e32 v195, v74, v195
	v_exp_f32_e32 v76, v76
	v_add_f32_e32 v195, v75, v195
	v_exp_f32_e32 v77, v77
	v_mfma_f32_32x32x16_bf16 v[16:31], v[36:39], v[236:239], v[16:31]
	v_add_f32_e32 v195, v76, v195
	v_exp_f32_e32 v78, v78
	v_add_f32_e32 v195, v77, v195
	v_exp_f32_e32 v79, v79
	v_add_f32_e32 v195, v78, v195
	v_add_f32_e32 v195, v79, v195
	s_waitcnt lgkmcnt(11)
	v_mfma_f32_32x32x16_bf16 v[48:63], v[172:175], v[100:103], 0
	v_exp_f32_e32 v80, v80
	v_exp_f32_e32 v81, v81
	v_exp_f32_e32 v82, v82
	s_waitcnt lgkmcnt(9)
	v_mfma_f32_32x32x16_bf16 v[32:47], v[180:183], v[100:103], 0
	v_add_f32_e32 v251, v80, v81
	v_cvt_pk_bf16_f32 v64, v64, v65
	v_exp_f32_e32 v83, v83
	v_add_f32_e32 v251, v82, v251
	v_mfma_f32_32x32x16_bf16 v[48:63], v[152:155], v[104:107], v[48:63]
	v_exp_f32_e32 v84, v84
	v_add_f32_e32 v251, v83, v251
	v_cvt_pk_bf16_f32 v65, v66, v67
	v_exp_f32_e32 v85, v85
	s_waitcnt lgkmcnt(8)
	v_mfma_f32_32x32x16_bf16 v[32:47], v[164:167], v[104:107], v[32:47]
	v_add_f32_e32 v251, v84, v251
	v_exp_f32_e32 v86, v86
	v_add_f32_e32 v251, v85, v251
	v_cvt_pk_bf16_f32 v66, v68, v69
	s_waitcnt lgkmcnt(7)
	v_mfma_f32_32x32x16_bf16 v[48:63], v[156:159], v[108:111], v[48:63]
	v_exp_f32_e32 v87, v87
	v_add_f32_e32 v251, v86, v251
	v_exp_f32_e32 v88, v88
	s_add_i32 s4, s90, 1
	s_cmp_lg_u32 s90, 2
	s_cselect_b32 s68, s4, 0
	s_mul_i32 s6, s68, 0x3400
	s_add_i32 s7, s6, 0
	s_add_u32 s98, s98, 0x3000
	s_addc_u32 s99, s99, 0

	v_add_u32_e32 v253, s7, v96
	s_waitcnt vmcnt(1)
	ds_write_b128 v253, v[128:131]
	s_and_saveexec_b64 s[4:5], s[2:3]
	v_add_u32_e32 v253, s7, v185
	ds_write_b128 v253, v[124:127]
	s_or_b64 exec, exec, s[4:5]
	v_lshl_add_u64 v[200:201], s[100:101], 0, v[204:205]

	s_waitcnt vmcnt(0)
	ds_write2_b64 v211, v[132:133], v[134:135] offset0:128 offset1:130
	v_lshl_add_u64 v[128:129], s[98:99], 0, v[98:99]
	s_nop 0
	global_load_dwordx4 v[128:131], v[128:129], off

	s_and_saveexec_b64 s[4:5], s[2:3]
	s_cbranch_execz .LatB_h1
	v_lshl_add_u64 v[124:125], s[98:99], 0, v[202:203]
	s_nop 0
	global_load_dwordx4 v[124:127], v[124:125], off
.LatB_h1:
	s_or_b64 exec, exec, s[4:5]
	global_load_dwordx4 v[132:135], v[200:201], off offset:384

	s_sub_u32 s98, s98, 0x3000
	s_subb_u32 s99, s99, 0

	s_waitcnt lgkmcnt(7)
	v_mfma_f32_32x32x16_bf16 v[32:47], v[176:179], v[108:111], v[32:47]
	v_add_f32_e32 v251, v87, v251
	v_cvt_pk_bf16_f32 v67, v70, v71
	v_exp_f32_e32 v89, v89
	v_add_f32_e32 v251, v88, v251
	v_mfma_f32_32x32x16_bf16 v[48:63], v[140:143], v[112:115], v[48:63]
	v_exp_f32_e32 v90, v90
	v_add_f32_e32 v251, v89, v251
	v_cvt_pk_bf16_f32 v68, v72, v73
	v_exp_f32_e32 v91, v91
	s_waitcnt lgkmcnt(6)
	v_mfma_f32_32x32x16_bf16 v[32:47], v[160:163], v[112:115], v[32:47]
	v_add_f32_e32 v251, v90, v251
	v_exp_f32_e32 v92, v92
	v_add_f32_e32 v251, v91, v251
	v_cvt_pk_bf16_f32 v69, v74, v75
	s_waitcnt lgkmcnt(5)
	v_mfma_f32_32x32x16_bf16 v[48:63], v[148:151], v[116:119], v[48:63]
	v_exp_f32_e32 v93, v93
	v_add_f32_e32 v251, v92, v251
	v_exp_f32_e32 v94, v94
	v_add_f32_e32 v251, v93, v251
	v_add_u32_e32 v196, v208, v184
	ds_read_b128 v[212:215], v196 offset:53760
	ds_read_b128 v[216:219], v196 offset:49152
	ds_read_b128 v[220:223], v196 offset:49184
	ds_read_b128 v[224:227], v196 offset:53792
	ds_read_b128 v[228:231], v196 offset:49216
	ds_read_b128 v[232:235], v196 offset:53824
	ds_read_b128 v[236:239], v196 offset:49248
	ds_read_b128 v[240:243], v196 offset:53856
	s_waitcnt lgkmcnt(11)
	v_mfma_f32_32x32x16_bf16 v[32:47], v[168:171], v[116:119], v[32:47]
	v_cvt_pk_bf16_f32 v70, v76, v77
	v_exp_f32_e32 v95, v95
	v_add_f32_e32 v251, v94, v251
	v_add_f32_e32 v251, v95, v251
	v_mfma_f32_32x32x16_bf16 v[48:63], v[136:139], v[120:123], v[48:63]
	v_cvt_pk_bf16_f32 v71, v78, v79
	v_cvt_pk_bf16_f32 v80, v80, v81
	v_cvt_pk_bf16_f32 v81, v82, v83
	v_cvt_pk_bf16_f32 v82, v84, v85
	v_cvt_pk_bf16_f32 v83, v86, v87
	v_cvt_pk_bf16_f32 v84, v88, v89
	s_waitcnt lgkmcnt(10)
	v_mfma_f32_32x32x16_bf16 v[32:47], v[144:147], v[120:123], v[32:47]
	v_cvt_pk_bf16_f32 v85, v90, v91
	v_cvt_pk_bf16_f32 v86, v92, v93
	v_cvt_pk_bf16_f32 v87, v94, v95
	v_add_f32_e32 v195, v195, v251
	v_add_f32_e32 v198, v198, v195
	s_add_i32 s40, s40, 2
	s_waitcnt lgkmcnt(0)
	s_barrier

	s_cmp_ge_u32 s40, s69
	s_cbranch_scc1 .LatB_yplain

	v_add_u32_e32 v197, s6, v209
	v_mfma_f32_32x32x16_bf16 v[0:15], v[64:67], v[212:215], v[0:15]
	ds_read_b128 v[172:175], v197
	ds_read_b128 v[152:155], v197 offset:32
	v_mfma_f32_32x32x16_bf16 v[0:15], v[68:71], v[224:227], v[0:15]
	ds_read_b128 v[180:183], v197 offset:6656
	ds_read_b128 v[164:167], v197 offset:6688
	v_mfma_f32_32x32x16_bf16 v[0:15], v[80:83], v[232:235], v[0:15]
	ds_read_b128 v[156:159], v197 offset:64
	ds_read_b128 v[140:143], v197 offset:96
	v_exp_f32_e32 v48, v48
	v_exp_f32_e32 v49, v49
	v_exp_f32_e32 v50, v50
	v_add_f32_e32 v195, v48, v49
	v_mfma_f32_32x32x16_bf16 v[0:15], v[84:87], v[240:243], v[0:15]
	ds_read_b128 v[176:179], v197 offset:6720
	ds_read_b128 v[160:163], v197 offset:6752
	v_exp_f32_e32 v51, v51
	v_add_f32_e32 v195, v50, v195
	v_exp_f32_e32 v52, v52
	v_add_f32_e32 v195, v51, v195
	v_exp_f32_e32 v53, v53
	v_add_f32_e32 v195, v52, v195
	v_mfma_f32_32x32x16_bf16 v[16:31], v[64:67], v[216:219], v[16:31]
	ds_read_b128 v[148:151], v197 offset:128
	ds_read_b128 v[136:139], v197 offset:160
	v_exp_f32_e32 v54, v54
	v_add_f32_e32 v195, v53, v195
	v_exp_f32_e32 v55, v55
	v_add_f32_e32 v195, v54, v195
	v_exp_f32_e32 v56, v56
	v_mfma_f32_32x32x16_bf16 v[16:31], v[68:71], v[220:223], v[16:31]
	ds_read_b128 v[168:171], v197 offset:6784
	ds_read_b128 v[144:147], v197 offset:6816
	v_add_f32_e32 v195, v55, v195
	v_exp_f32_e32 v57, v57
	v_add_f32_e32 v195, v56, v195
	v_exp_f32_e32 v58, v58
	v_add_f32_e32 v195, v57, v195
	v_mfma_f32_32x32x16_bf16 v[16:31], v[80:83], v[228:231], v[16:31]
	v_exp_f32_e32 v59, v59
	v_add_f32_e32 v195, v58, v195
	v_exp_f32_e32 v60, v60
	v_add_f32_e32 v195, v59, v195
	v_exp_f32_e32 v61, v61
	v_mfma_f32_32x32x16_bf16 v[16:31], v[84:87], v[236:239], v[16:31]
	v_add_f32_e32 v195, v60, v195
	v_exp_f32_e32 v62, v62
	v_add_f32_e32 v195, v61, v195
	v_exp_f32_e32 v63, v63
	v_add_f32_e32 v195, v62, v195
	v_add_f32_e32 v195, v63, v195
	s_branch .LatB_ctl
.LatB_yplain:
	v_add_u32_e32 v197, s6, v209
	v_mfma_f32_32x32x16_bf16 v[0:15], v[64:67], v[212:215], v[0:15]
	ds_read_b128 v[172:175], v197
	ds_read_b128 v[152:155], v197 offset:32
	v_mfma_f32_32x32x16_bf16 v[0:15], v[68:71], v[224:227], v[0:15]
	ds_read_b128 v[180:183], v197 offset:6656
	ds_read_b128 v[164:167], v197 offset:6688
	v_mfma_f32_32x32x16_bf16 v[0:15], v[80:83], v[232:235], v[0:15]
	ds_read_b128 v[156:159], v197 offset:64
	ds_read_b128 v[140:143], v197 offset:96
	v_mfma_f32_32x32x16_bf16 v[0:15], v[84:87], v[240:243], v[0:15]
	ds_read_b128 v[176:179], v197 offset:6720
	ds_read_b128 v[160:163], v197 offset:6752
	v_mfma_f32_32x32x16_bf16 v[16:31], v[64:67], v[216:219], v[16:31]
	ds_read_b128 v[148:151], v197 offset:128
	ds_read_b128 v[136:139], v197 offset:160
	v_mfma_f32_32x32x16_bf16 v[16:31], v[68:71], v[220:223], v[16:31]
	ds_read_b128 v[168:171], v197 offset:6784
	ds_read_b128 v[144:147], v197 offset:6816
	v_mfma_f32_32x32x16_bf16 v[16:31], v[80:83], v[228:231], v[16:31]
	v_mfma_f32_32x32x16_bf16 v[16:31], v[84:87], v[236:239], v[16:31]
